# epilogue yield, s_sleep 50 between row groups for workgroups without a split-K piece
# baseline (speedup 1.0000x reference)
.LBB0_1163:
	s_ashr_i32 s17, s54, 3
	s_mul_hi_i32 s19, s17, 0x9000
	s_mul_i32 s17, s17, 0x9000
	s_add_u32 s26, s10, s17
	s_addc_u32 s27, s11, s19
	v_lshl_add_u64 v[162:163], s[26:27], 0, v[160:161]
	global_load_dwordx4 v[64:67], v[162:163], off
	v_readlane_b32 s26, v255, 5
	v_readlane_b32 s27, v255, 6
	s_lshl_b32 s17, s54, 8
	v_add_u32_e32 v194, s17, v151
	v_lshl_add_u64 v[166:167], s[26:27], 0, v[160:161]
	v_readlane_b32 s26, v255, 9
	v_readlane_b32 s27, v255, 10
	v_ashrrev_i32_e32 v195, 31, v194
	v_lshl_add_u64 v[212:213], v[194:195], 3, s[12:13]
	v_lshl_add_u64 v[168:169], s[26:27], 0, v[160:161]
	v_lshlrev_b64 v[214:215], 12, v[194:195]
	v_lshl_add_u64 v[214:215], s[0:1], 0, v[214:215]
	v_lshl_add_u64 v[214:215], v[214:215], 0, v[160:161]
	s_waitcnt vmcnt(0)
	v_pk_add_f32 v[178:179], v[66:67], 1.0 op_sel_hi:[1,0]
	v_pk_add_f32 v[180:181], v[64:65], 1.0 op_sel_hi:[1,0]
	global_load_dwordx4 v[84:87], v[166:167], off
	global_load_dwordx4 v[64:67], v[168:169], off
	s_waitcnt vmcnt(0)
	v_pk_mul_f32 v[190:191], v[66:67], s[58:59] op_sel_hi:[1,0]
	v_pk_mul_f32 v[192:193], v[64:65], s[58:59] op_sel_hi:[1,0]
	global_load_dwordx4 v[64:67], v[162:163], off offset:64
	s_waitcnt vmcnt(0)
	v_pk_add_f32 v[174:175], v[66:67], 1.0 op_sel_hi:[1,0]
	v_pk_add_f32 v[176:177], v[64:65], 1.0 op_sel_hi:[1,0]
	global_load_dwordx4 v[72:75], v[166:167], off offset:64
	global_load_dwordx4 v[64:67], v[168:169], off offset:64
	s_waitcnt vmcnt(0)
	v_pk_mul_f32 v[186:187], v[66:67], s[58:59] op_sel_hi:[1,0]
	v_pk_mul_f32 v[188:189], v[64:65], s[58:59] op_sel_hi:[1,0]
	global_load_dwordx4 v[64:67], v[162:163], off offset:512
	s_waitcnt vmcnt(0)
	v_pk_add_f32 v[170:171], v[66:67], 1.0 op_sel_hi:[1,0]
	v_pk_add_f32 v[172:173], v[64:65], 1.0 op_sel_hi:[1,0]
	global_load_dwordx4 v[68:71], v[166:167], off offset:512
	global_load_dwordx4 v[64:67], v[168:169], off offset:512
	s_waitcnt vmcnt(0)
	v_pk_mul_f32 v[182:183], v[66:67], s[58:59] op_sel_hi:[1,0]
	v_pk_mul_f32 v[184:185], v[64:65], s[58:59] op_sel_hi:[1,0]
	global_load_dwordx4 v[64:67], v[162:163], off offset:576
	s_waitcnt vmcnt(0)
	v_pk_add_f32 v[162:163], v[66:67], 1.0 op_sel_hi:[1,0]
	v_pk_add_f32 v[164:165], v[64:65], 1.0 op_sel_hi:[1,0]
	global_load_dwordx4 v[64:67], v[166:167], off offset:576
	global_load_dwordx4 v[232:235], v[168:169], off offset:576
	s_waitcnt vmcnt(0)
	v_pk_mul_f32 v[166:167], v[234:235], s[58:59] op_sel_hi:[1,0]
	global_load_dwordx2 v[212:213], v[212:213], off
	v_pk_mul_f32 v[168:169], v[232:233], s[58:59] op_sel_hi:[1,0]
	global_load_dwordx4 v[232:235], v[214:215], off
	global_load_dwordx4 v[236:239], v[214:215], off offset:64
	global_load_dwordx4 v[240:243], v[214:215], off offset:512
	global_load_dwordx4 v[244:247], v[214:215], off offset:576
	s_waitcnt vmcnt(4)
	v_mul_f32_e32 v216, 0x3fb504f3, v213
	s_waitcnt vmcnt(3)
	v_sub_f32_e32 v219, v233, v212
	v_sub_f32_e32 v218, v232, v212
	v_sub_f32_e32 v233, v235, v212
	v_sub_f32_e32 v232, v234, v212
	v_pk_mul_f32 v[232:233], v[232:233], v[216:217] op_sel_hi:[1,0]
	v_pk_mul_f32 v[218:219], v[218:219], v[216:217] op_sel_hi:[1,0]
	v_pk_fma_f32 v[232:233], v[86:87], v[232:233], v[190:191]
	v_pk_fma_f32 v[218:219], v[84:85], v[218:219], v[192:193]
	v_pk_fma_f32 v[142:143], v[142:143], v[178:179], v[232:233]
	v_pk_fma_f32 v[140:141], v[140:141], v[180:181], v[218:219]
	global_store_dwordx4 v[214:215], v[140:143], off
	s_waitcnt vmcnt(3)
	s_nop 0
	v_sub_f32_e32 v141, v237, v212
	v_sub_f32_e32 v140, v236, v212
	v_sub_f32_e32 v143, v239, v212
	v_sub_f32_e32 v142, v238, v212
	v_pk_mul_f32 v[142:143], v[142:143], v[216:217] op_sel_hi:[1,0]
	v_pk_mul_f32 v[140:141], v[140:141], v[216:217] op_sel_hi:[1,0]
	v_pk_fma_f32 v[142:143], v[74:75], v[142:143], v[186:187]
	v_pk_fma_f32 v[140:141], v[72:73], v[140:141], v[188:189]
	v_pk_fma_f32 v[138:139], v[138:139], v[174:175], v[142:143]
	v_pk_fma_f32 v[136:137], v[136:137], v[176:177], v[140:141]
	global_store_dwordx4 v[214:215], v[136:139], off offset:64
	s_waitcnt vmcnt(3)
	s_nop 0
	v_sub_f32_e32 v137, v241, v212
	v_sub_f32_e32 v136, v240, v212
	v_sub_f32_e32 v139, v243, v212
	v_sub_f32_e32 v138, v242, v212
	v_pk_mul_f32 v[138:139], v[216:217], v[138:139] op_sel_hi:[0,1]
	v_pk_mul_f32 v[136:137], v[216:217], v[136:137] op_sel_hi:[0,1]
	v_pk_fma_f32 v[136:137], v[68:69], v[136:137], v[184:185]
	v_pk_fma_f32 v[138:139], v[70:71], v[138:139], v[182:183]
	v_pk_fma_f32 v[132:133], v[132:133], v[172:173], v[136:137]
	v_pk_fma_f32 v[134:135], v[134:135], v[170:171], v[138:139]
	global_store_dwordx4 v[214:215], v[132:135], off offset:512
	s_waitcnt vmcnt(3)
	s_nop 0
	v_sub_f32_e32 v133, v245, v212
	v_sub_f32_e32 v132, v244, v212
	v_sub_f32_e32 v135, v247, v212
	v_sub_f32_e32 v134, v246, v212
	v_pk_mul_f32 v[134:135], v[216:217], v[134:135] op_sel_hi:[0,1]
	v_pk_mul_f32 v[132:133], v[216:217], v[132:133] op_sel_hi:[0,1]
	v_pk_fma_f32 v[132:133], v[64:65], v[132:133], v[168:169]
	v_pk_fma_f32 v[134:135], v[66:67], v[134:135], v[166:167]
	v_pk_fma_f32 v[128:129], v[128:129], v[164:165], v[132:133]
	v_pk_fma_f32 v[130:131], v[130:131], v[162:163], v[134:135]
	global_store_dwordx4 v[214:215], v[128:131], off offset:576
	s_and_b64 vcc, exec, s[6:7]
	s_cbranch_vccnz .Lmy_epi_w0
	s_sleep 50
.Lmy_epi_w0:
	s_nop 1
	v_add_u32_e32 v128, s17, v226
	v_ashrrev_i32_e32 v129, 31, v128
	v_lshl_add_u64 v[130:131], v[128:129], 3, s[12:13]
	global_load_dwordx2 v[212:213], v[130:131], off
	v_lshlrev_b64 v[128:129], 12, v[128:129]
	v_lshl_add_u64 v[128:129], s[0:1], 0, v[128:129]
	v_lshl_add_u64 v[214:215], v[128:129], 0, v[160:161]
	global_load_dwordx4 v[128:131], v[214:215], off
	global_load_dwordx4 v[132:135], v[214:215], off offset:64
	global_load_dwordx4 v[136:139], v[214:215], off offset:512
	global_load_dwordx4 v[140:143], v[214:215], off offset:576
	s_waitcnt vmcnt(4)
	v_mul_f32_e32 v216, 0x3fb504f3, v213
	s_waitcnt vmcnt(3)
	v_sub_f32_e32 v129, v129, v212
	v_sub_f32_e32 v128, v128, v212
	v_sub_f32_e32 v131, v131, v212
	v_sub_f32_e32 v130, v130, v212
	v_pk_mul_f32 v[130:131], v[130:131], v[216:217] op_sel_hi:[1,0]
	v_pk_mul_f32 v[128:129], v[128:129], v[216:217] op_sel_hi:[1,0]
	v_pk_fma_f32 v[130:131], v[86:87], v[130:131], v[190:191]
	v_pk_fma_f32 v[128:129], v[84:85], v[128:129], v[192:193]
	v_pk_fma_f32 v[126:127], v[126:127], v[178:179], v[130:131]
	v_pk_fma_f32 v[124:125], v[124:125], v[180:181], v[128:129]
	global_store_dwordx4 v[214:215], v[124:127], off
	s_waitcnt vmcnt(3)
	s_nop 0
	v_sub_f32_e32 v125, v133, v212
	v_sub_f32_e32 v124, v132, v212
	v_sub_f32_e32 v127, v135, v212
	v_sub_f32_e32 v126, v134, v212
	v_pk_mul_f32 v[126:127], v[126:127], v[216:217] op_sel_hi:[1,0]
	v_pk_mul_f32 v[124:125], v[124:125], v[216:217] op_sel_hi:[1,0]
	v_pk_fma_f32 v[126:127], v[74:75], v[126:127], v[186:187]
	v_pk_fma_f32 v[124:125], v[72:73], v[124:125], v[188:189]
	v_pk_fma_f32 v[122:123], v[122:123], v[174:175], v[126:127]
	v_pk_fma_f32 v[120:121], v[120:121], v[176:177], v[124:125]
	global_store_dwordx4 v[214:215], v[120:123], off offset:64
	s_waitcnt vmcnt(3)
	s_nop 0
	v_sub_f32_e32 v121, v137, v212
	v_sub_f32_e32 v120, v136, v212
	v_sub_f32_e32 v123, v139, v212
	v_sub_f32_e32 v122, v138, v212
	v_pk_mul_f32 v[122:123], v[216:217], v[122:123] op_sel_hi:[0,1]
	v_pk_mul_f32 v[120:121], v[216:217], v[120:121] op_sel_hi:[0,1]
	v_pk_fma_f32 v[120:121], v[68:69], v[120:121], v[184:185]
	v_pk_fma_f32 v[122:123], v[70:71], v[122:123], v[182:183]
	v_pk_fma_f32 v[116:117], v[116:117], v[172:173], v[120:121]
	v_pk_fma_f32 v[118:119], v[118:119], v[170:171], v[122:123]
	global_store_dwordx4 v[214:215], v[116:119], off offset:512
	s_waitcnt vmcnt(3)
	s_nop 0
	v_sub_f32_e32 v117, v141, v212
	v_sub_f32_e32 v116, v140, v212
	v_sub_f32_e32 v119, v143, v212
	v_sub_f32_e32 v118, v142, v212
	v_pk_mul_f32 v[118:119], v[216:217], v[118:119] op_sel_hi:[0,1]
	v_pk_mul_f32 v[116:117], v[216:217], v[116:117] op_sel_hi:[0,1]
	v_pk_fma_f32 v[116:117], v[64:65], v[116:117], v[168:169]
	v_pk_fma_f32 v[118:119], v[66:67], v[118:119], v[166:167]
	v_pk_fma_f32 v[112:113], v[112:113], v[164:165], v[116:117]
	v_pk_fma_f32 v[114:115], v[114:115], v[162:163], v[118:119]
	global_store_dwordx4 v[214:215], v[112:115], off offset:576
	s_and_b64 vcc, exec, s[6:7]
	s_cbranch_vccnz .Lmy_epi_w1
	s_sleep 50
.Lmy_epi_w1:
	s_nop 1
	v_add_u32_e32 v112, s17, v227
	v_ashrrev_i32_e32 v113, 31, v112
	v_lshl_add_u64 v[114:115], v[112:113], 3, s[12:13]
	global_load_dwordx2 v[128:129], v[114:115], off
	v_lshlrev_b64 v[112:113], 12, v[112:113]
	v_lshl_add_u64 v[112:113], s[0:1], 0, v[112:113]
	v_lshl_add_u64 v[130:131], v[112:113], 0, v[160:161]
	global_load_dwordx4 v[112:115], v[130:131], off
	global_load_dwordx4 v[116:119], v[130:131], off offset:64
	global_load_dwordx4 v[120:123], v[130:131], off offset:512
	global_load_dwordx4 v[124:127], v[130:131], off offset:576
	s_waitcnt vmcnt(4)
	v_mul_f32_e32 v132, 0x3fb504f3, v129
	s_waitcnt vmcnt(3)
	v_sub_f32_e32 v113, v113, v128
	v_sub_f32_e32 v112, v112, v128
	v_sub_f32_e32 v115, v115, v128
	v_sub_f32_e32 v114, v114, v128
	v_pk_mul_f32 v[114:115], v[114:115], v[132:133] op_sel_hi:[1,0]
	v_pk_mul_f32 v[112:113], v[112:113], v[132:133] op_sel_hi:[1,0]
	v_pk_fma_f32 v[114:115], v[86:87], v[114:115], v[190:191]
	v_pk_fma_f32 v[112:113], v[84:85], v[112:113], v[192:193]
	v_pk_fma_f32 v[110:111], v[110:111], v[178:179], v[114:115]
	v_pk_fma_f32 v[108:109], v[108:109], v[180:181], v[112:113]
	global_store_dwordx4 v[130:131], v[108:111], off
	s_waitcnt vmcnt(3)
	s_nop 0
	v_sub_f32_e32 v109, v117, v128
	v_sub_f32_e32 v108, v116, v128
	v_sub_f32_e32 v111, v119, v128
	v_sub_f32_e32 v110, v118, v128
	v_pk_mul_f32 v[110:111], v[110:111], v[132:133] op_sel_hi:[1,0]
	v_pk_mul_f32 v[108:109], v[108:109], v[132:133] op_sel_hi:[1,0]
	v_pk_fma_f32 v[110:111], v[74:75], v[110:111], v[186:187]
	v_pk_fma_f32 v[108:109], v[72:73], v[108:109], v[188:189]
	v_pk_fma_f32 v[106:107], v[106:107], v[174:175], v[110:111]
	v_pk_fma_f32 v[104:105], v[104:105], v[176:177], v[108:109]
	global_store_dwordx4 v[130:131], v[104:107], off offset:64
	s_waitcnt vmcnt(3)
	s_nop 0
	v_sub_f32_e32 v105, v121, v128
	v_sub_f32_e32 v104, v120, v128
	v_sub_f32_e32 v107, v123, v128
	v_sub_f32_e32 v106, v122, v128
	v_pk_mul_f32 v[106:107], v[132:133], v[106:107] op_sel_hi:[0,1]
	v_pk_mul_f32 v[104:105], v[132:133], v[104:105] op_sel_hi:[0,1]
	v_pk_fma_f32 v[104:105], v[68:69], v[104:105], v[184:185]
	v_pk_fma_f32 v[106:107], v[70:71], v[106:107], v[182:183]
	v_pk_fma_f32 v[100:101], v[100:101], v[172:173], v[104:105]
	v_pk_fma_f32 v[102:103], v[102:103], v[170:171], v[106:107]
	global_store_dwordx4 v[130:131], v[100:103], off offset:512
	s_waitcnt vmcnt(3)
	s_nop 0
	v_sub_f32_e32 v101, v125, v128
	v_sub_f32_e32 v100, v124, v128
	v_sub_f32_e32 v103, v127, v128
	v_sub_f32_e32 v102, v126, v128
	v_pk_mul_f32 v[102:103], v[132:133], v[102:103] op_sel_hi:[0,1]
	v_pk_mul_f32 v[100:101], v[132:133], v[100:101] op_sel_hi:[0,1]
	v_pk_fma_f32 v[100:101], v[64:65], v[100:101], v[168:169]
	v_pk_fma_f32 v[102:103], v[66:67], v[102:103], v[166:167]
	v_pk_fma_f32 v[96:97], v[96:97], v[164:165], v[100:101]
	v_pk_fma_f32 v[98:99], v[98:99], v[162:163], v[102:103]
	global_store_dwordx4 v[130:131], v[96:99], off offset:576
	s_and_b64 vcc, exec, s[6:7]
	s_cbranch_vccnz .Lmy_epi_w2
	s_sleep 50
.Lmy_epi_w2:
	s_nop 1
	v_add_u32_e32 v96, s17, v228
	v_ashrrev_i32_e32 v97, 31, v96
	v_lshl_add_u64 v[98:99], v[96:97], 3, s[12:13]
	global_load_dwordx2 v[112:113], v[98:99], off
	v_lshlrev_b64 v[96:97], 12, v[96:97]
	v_lshl_add_u64 v[96:97], s[0:1], 0, v[96:97]
	v_lshl_add_u64 v[114:115], v[96:97], 0, v[160:161]
	global_load_dwordx4 v[96:99], v[114:115], off
	global_load_dwordx4 v[100:103], v[114:115], off offset:64
	global_load_dwordx4 v[104:107], v[114:115], off offset:512
	global_load_dwordx4 v[108:111], v[114:115], off offset:576
	s_waitcnt vmcnt(4)
	v_mul_f32_e32 v116, 0x3fb504f3, v113
	s_waitcnt vmcnt(3)
	v_sub_f32_e32 v97, v97, v112
	v_sub_f32_e32 v96, v96, v112
	v_sub_f32_e32 v99, v99, v112
	v_sub_f32_e32 v98, v98, v112
	v_pk_mul_f32 v[98:99], v[98:99], v[116:117] op_sel_hi:[1,0]
	v_pk_mul_f32 v[96:97], v[96:97], v[116:117] op_sel_hi:[1,0]
	v_pk_fma_f32 v[98:99], v[86:87], v[98:99], v[190:191]
	v_pk_fma_f32 v[96:97], v[84:85], v[96:97], v[192:193]
	v_pk_fma_f32 v[94:95], v[94:95], v[178:179], v[98:99]
	v_pk_fma_f32 v[92:93], v[92:93], v[180:181], v[96:97]
	global_store_dwordx4 v[114:115], v[92:95], off
	s_waitcnt vmcnt(3)
	s_nop 0
	v_sub_f32_e32 v93, v101, v112
	v_sub_f32_e32 v92, v100, v112
	v_sub_f32_e32 v95, v103, v112
	v_sub_f32_e32 v94, v102, v112
	v_pk_mul_f32 v[94:95], v[94:95], v[116:117] op_sel_hi:[1,0]
	v_pk_mul_f32 v[92:93], v[92:93], v[116:117] op_sel_hi:[1,0]
	v_pk_fma_f32 v[94:95], v[74:75], v[94:95], v[186:187]
	v_pk_fma_f32 v[92:93], v[72:73], v[92:93], v[188:189]
	v_pk_fma_f32 v[90:91], v[90:91], v[174:175], v[94:95]
	v_pk_fma_f32 v[88:89], v[88:89], v[176:177], v[92:93]
	global_store_dwordx4 v[114:115], v[88:91], off offset:64
	s_waitcnt vmcnt(3)
	s_nop 0
	v_sub_f32_e32 v89, v105, v112
	v_sub_f32_e32 v88, v104, v112
	v_sub_f32_e32 v91, v107, v112
	v_sub_f32_e32 v90, v106, v112
	v_pk_mul_f32 v[90:91], v[116:117], v[90:91] op_sel_hi:[0,1]
	v_pk_mul_f32 v[88:89], v[116:117], v[88:89] op_sel_hi:[0,1]
	v_pk_fma_f32 v[88:89], v[68:69], v[88:89], v[184:185]
	v_pk_fma_f32 v[90:91], v[70:71], v[90:91], v[182:183]
	v_pk_fma_f32 v[80:81], v[80:81], v[172:173], v[88:89]
	v_pk_fma_f32 v[82:83], v[82:83], v[170:171], v[90:91]
	global_store_dwordx4 v[114:115], v[80:83], off offset:512
	s_waitcnt vmcnt(3)
	s_nop 0
	v_sub_f32_e32 v81, v109, v112
	v_sub_f32_e32 v80, v108, v112
	v_sub_f32_e32 v83, v111, v112
	v_sub_f32_e32 v82, v110, v112
	v_pk_mul_f32 v[82:83], v[116:117], v[82:83] op_sel_hi:[0,1]
	v_pk_mul_f32 v[80:81], v[116:117], v[80:81] op_sel_hi:[0,1]
	v_pk_fma_f32 v[80:81], v[64:65], v[80:81], v[168:169]
	v_pk_fma_f32 v[82:83], v[66:67], v[82:83], v[166:167]
	v_pk_fma_f32 v[76:77], v[76:77], v[164:165], v[80:81]
	v_pk_fma_f32 v[78:79], v[78:79], v[162:163], v[82:83]
	global_store_dwordx4 v[114:115], v[76:79], off offset:576
	s_and_b64 vcc, exec, s[6:7]
	s_cbranch_vccnz .Lmy_epi_w3
	s_sleep 50
.Lmy_epi_w3:
	s_nop 1
	v_add_u32_e32 v76, 0x80, v194
	v_ashrrev_i32_e32 v77, 31, v76
	v_lshl_add_u64 v[78:79], v[76:77], 3, s[12:13]
	global_load_dwordx2 v[96:97], v[78:79], off
	v_lshlrev_b64 v[76:77], 12, v[76:77]
	v_lshl_add_u64 v[76:77], s[0:1], 0, v[76:77]
	v_lshl_add_u64 v[98:99], v[76:77], 0, v[160:161]
	global_load_dwordx4 v[76:79], v[98:99], off
	global_load_dwordx4 v[80:83], v[98:99], off offset:64
	global_load_dwordx4 v[88:91], v[98:99], off offset:512
	global_load_dwordx4 v[92:95], v[98:99], off offset:576
	s_waitcnt vmcnt(4)
	v_mul_f32_e32 v100, 0x3fb504f3, v97
	s_waitcnt vmcnt(3)
	v_sub_f32_e32 v77, v77, v96
	v_sub_f32_e32 v76, v76, v96
	v_sub_f32_e32 v79, v79, v96
	v_sub_f32_e32 v78, v78, v96
	v_pk_mul_f32 v[78:79], v[78:79], v[100:101] op_sel_hi:[1,0]
	v_pk_mul_f32 v[76:77], v[76:77], v[100:101] op_sel_hi:[1,0]
	v_pk_fma_f32 v[78:79], v[86:87], v[78:79], v[190:191]
	v_pk_fma_f32 v[76:77], v[84:85], v[76:77], v[192:193]
	v_pk_fma_f32 v[62:63], v[62:63], v[178:179], v[78:79]
	v_pk_fma_f32 v[60:61], v[60:61], v[180:181], v[76:77]
	global_store_dwordx4 v[98:99], v[60:63], off
	s_waitcnt vmcnt(3)
	s_nop 0
	v_sub_f32_e32 v61, v81, v96
	v_sub_f32_e32 v60, v80, v96
	v_sub_f32_e32 v63, v83, v96
	v_sub_f32_e32 v62, v82, v96
	v_pk_mul_f32 v[62:63], v[62:63], v[100:101] op_sel_hi:[1,0]
	v_pk_mul_f32 v[60:61], v[60:61], v[100:101] op_sel_hi:[1,0]
	v_pk_fma_f32 v[62:63], v[74:75], v[62:63], v[186:187]
	v_pk_fma_f32 v[60:61], v[72:73], v[60:61], v[188:189]
	v_pk_fma_f32 v[58:59], v[58:59], v[174:175], v[62:63]
	v_pk_fma_f32 v[56:57], v[56:57], v[176:177], v[60:61]
	global_store_dwordx4 v[98:99], v[56:59], off offset:64
	s_waitcnt vmcnt(3)
	s_nop 0
	v_sub_f32_e32 v57, v89, v96
	v_sub_f32_e32 v56, v88, v96
	v_sub_f32_e32 v59, v91, v96
	v_sub_f32_e32 v58, v90, v96
	v_pk_mul_f32 v[58:59], v[100:101], v[58:59] op_sel_hi:[0,1]
	v_pk_mul_f32 v[56:57], v[100:101], v[56:57] op_sel_hi:[0,1]
	v_pk_fma_f32 v[56:57], v[68:69], v[56:57], v[184:185]
	v_pk_fma_f32 v[58:59], v[70:71], v[58:59], v[182:183]
	v_pk_fma_f32 v[52:53], v[52:53], v[172:173], v[56:57]
	v_pk_fma_f32 v[54:55], v[54:55], v[170:171], v[58:59]
	global_store_dwordx4 v[98:99], v[52:55], off offset:512
	s_waitcnt vmcnt(3)
	s_nop 0
	v_sub_f32_e32 v53, v93, v96
	v_sub_f32_e32 v52, v92, v96
	v_sub_f32_e32 v55, v95, v96
	v_sub_f32_e32 v54, v94, v96
	v_pk_mul_f32 v[54:55], v[100:101], v[54:55] op_sel_hi:[0,1]
	v_pk_mul_f32 v[52:53], v[100:101], v[52:53] op_sel_hi:[0,1]
	v_pk_fma_f32 v[52:53], v[64:65], v[52:53], v[168:169]
	v_pk_fma_f32 v[54:55], v[66:67], v[54:55], v[166:167]
	v_pk_fma_f32 v[48:49], v[48:49], v[164:165], v[52:53]
	v_pk_fma_f32 v[50:51], v[50:51], v[162:163], v[54:55]
	global_store_dwordx4 v[98:99], v[48:51], off offset:576
	s_and_b64 vcc, exec, s[6:7]
	s_cbranch_vccnz .Lmy_epi_w4
	s_sleep 50
.Lmy_epi_w4:
	s_nop 1
	v_add_u32_e32 v48, 0x90, v194
	v_ashrrev_i32_e32 v49, 31, v48
	v_lshl_add_u64 v[50:51], v[48:49], 3, s[12:13]
	global_load_dwordx2 v[76:77], v[50:51], off
	v_lshlrev_b64 v[48:49], 12, v[48:49]
	v_lshl_add_u64 v[48:49], s[0:1], 0, v[48:49]
	v_lshl_add_u64 v[78:79], v[48:49], 0, v[160:161]
	global_load_dwordx4 v[48:51], v[78:79], off
	global_load_dwordx4 v[52:55], v[78:79], off offset:64
	global_load_dwordx4 v[56:59], v[78:79], off offset:512
	global_load_dwordx4 v[60:63], v[78:79], off offset:576
	s_waitcnt vmcnt(4)
	v_mul_f32_e32 v80, 0x3fb504f3, v77
	s_waitcnt vmcnt(3)
	v_sub_f32_e32 v49, v49, v76
	v_sub_f32_e32 v48, v48, v76
	v_sub_f32_e32 v51, v51, v76
	v_sub_f32_e32 v50, v50, v76
	v_pk_mul_f32 v[50:51], v[50:51], v[80:81] op_sel_hi:[1,0]
	v_pk_mul_f32 v[48:49], v[48:49], v[80:81] op_sel_hi:[1,0]
	v_pk_fma_f32 v[50:51], v[86:87], v[50:51], v[190:191]
	v_pk_fma_f32 v[48:49], v[84:85], v[48:49], v[192:193]
	v_pk_fma_f32 v[46:47], v[46:47], v[178:179], v[50:51]
	v_pk_fma_f32 v[44:45], v[44:45], v[180:181], v[48:49]
	global_store_dwordx4 v[78:79], v[44:47], off
	s_waitcnt vmcnt(3)
	s_nop 0
	v_sub_f32_e32 v45, v53, v76
	v_sub_f32_e32 v44, v52, v76
	v_sub_f32_e32 v47, v55, v76
	v_sub_f32_e32 v46, v54, v76
	v_pk_mul_f32 v[46:47], v[46:47], v[80:81] op_sel_hi:[1,0]
	v_pk_mul_f32 v[44:45], v[44:45], v[80:81] op_sel_hi:[1,0]
	v_pk_fma_f32 v[46:47], v[74:75], v[46:47], v[186:187]
	v_pk_fma_f32 v[44:45], v[72:73], v[44:45], v[188:189]
	v_pk_fma_f32 v[42:43], v[42:43], v[174:175], v[46:47]
	v_pk_fma_f32 v[40:41], v[40:41], v[176:177], v[44:45]
	global_store_dwordx4 v[78:79], v[40:43], off offset:64
	s_waitcnt vmcnt(3)
	s_nop 0
	v_sub_f32_e32 v41, v57, v76
	v_sub_f32_e32 v40, v56, v76
	v_sub_f32_e32 v43, v59, v76
	v_sub_f32_e32 v42, v58, v76
	v_pk_mul_f32 v[42:43], v[80:81], v[42:43] op_sel_hi:[0,1]
	v_pk_mul_f32 v[40:41], v[80:81], v[40:41] op_sel_hi:[0,1]
	v_pk_fma_f32 v[40:41], v[68:69], v[40:41], v[184:185]
	v_pk_fma_f32 v[42:43], v[70:71], v[42:43], v[182:183]
	v_pk_fma_f32 v[36:37], v[36:37], v[172:173], v[40:41]
	v_pk_fma_f32 v[38:39], v[38:39], v[170:171], v[42:43]
	global_store_dwordx4 v[78:79], v[36:39], off offset:512
	s_waitcnt vmcnt(3)
	s_nop 0
	v_sub_f32_e32 v37, v61, v76
	v_sub_f32_e32 v36, v60, v76
	v_sub_f32_e32 v39, v63, v76
	v_sub_f32_e32 v38, v62, v76
	v_pk_mul_f32 v[38:39], v[80:81], v[38:39] op_sel_hi:[0,1]
	v_pk_mul_f32 v[36:37], v[80:81], v[36:37] op_sel_hi:[0,1]
	v_pk_fma_f32 v[36:37], v[64:65], v[36:37], v[168:169]
	v_pk_fma_f32 v[38:39], v[66:67], v[38:39], v[166:167]
	v_pk_fma_f32 v[32:33], v[32:33], v[164:165], v[36:37]
	v_pk_fma_f32 v[34:35], v[34:35], v[162:163], v[38:39]
	global_store_dwordx4 v[78:79], v[32:35], off offset:576
	s_and_b64 vcc, exec, s[6:7]
	s_cbranch_vccnz .Lmy_epi_w5
	s_sleep 50
.Lmy_epi_w5:
	s_nop 1
	v_add_u32_e32 v32, 0xa0, v194
	v_ashrrev_i32_e32 v33, 31, v32
	v_lshl_add_u64 v[34:35], v[32:33], 3, s[12:13]
	global_load_dwordx2 v[48:49], v[34:35], off
	v_lshlrev_b64 v[32:33], 12, v[32:33]
	v_lshl_add_u64 v[32:33], s[0:1], 0, v[32:33]
	v_lshl_add_u64 v[50:51], v[32:33], 0, v[160:161]
	global_load_dwordx4 v[32:35], v[50:51], off
	global_load_dwordx4 v[36:39], v[50:51], off offset:64
	global_load_dwordx4 v[40:43], v[50:51], off offset:512
	global_load_dwordx4 v[44:47], v[50:51], off offset:576
	s_waitcnt vmcnt(4)
	v_mul_f32_e32 v52, 0x3fb504f3, v49
	s_waitcnt vmcnt(3)
	v_sub_f32_e32 v33, v33, v48
	v_sub_f32_e32 v32, v32, v48
	v_sub_f32_e32 v35, v35, v48
	v_sub_f32_e32 v34, v34, v48
	v_pk_mul_f32 v[34:35], v[34:35], v[52:53] op_sel_hi:[1,0]
	v_pk_mul_f32 v[32:33], v[32:33], v[52:53] op_sel_hi:[1,0]
	v_pk_fma_f32 v[34:35], v[86:87], v[34:35], v[190:191]
	v_pk_fma_f32 v[32:33], v[84:85], v[32:33], v[192:193]
	v_pk_fma_f32 v[30:31], v[30:31], v[178:179], v[34:35]
	v_pk_fma_f32 v[28:29], v[28:29], v[180:181], v[32:33]
	global_store_dwordx4 v[50:51], v[28:31], off
	s_waitcnt vmcnt(3)
	s_nop 0
	v_sub_f32_e32 v29, v37, v48
	v_sub_f32_e32 v28, v36, v48
	v_sub_f32_e32 v31, v39, v48
	v_sub_f32_e32 v30, v38, v48
	v_pk_mul_f32 v[30:31], v[30:31], v[52:53] op_sel_hi:[1,0]
	v_pk_mul_f32 v[28:29], v[28:29], v[52:53] op_sel_hi:[1,0]
	v_pk_fma_f32 v[30:31], v[74:75], v[30:31], v[186:187]
	v_pk_fma_f32 v[28:29], v[72:73], v[28:29], v[188:189]
	v_pk_fma_f32 v[26:27], v[26:27], v[174:175], v[30:31]
	v_pk_fma_f32 v[24:25], v[24:25], v[176:177], v[28:29]
	global_store_dwordx4 v[50:51], v[24:27], off offset:64
	s_waitcnt vmcnt(3)
	s_nop 0
	v_sub_f32_e32 v25, v41, v48
	v_sub_f32_e32 v24, v40, v48
	v_sub_f32_e32 v27, v43, v48
	v_sub_f32_e32 v26, v42, v48
	v_pk_mul_f32 v[26:27], v[52:53], v[26:27] op_sel_hi:[0,1]
	v_pk_mul_f32 v[24:25], v[52:53], v[24:25] op_sel_hi:[0,1]
	v_pk_fma_f32 v[24:25], v[68:69], v[24:25], v[184:185]
	v_pk_fma_f32 v[26:27], v[70:71], v[26:27], v[182:183]
	v_pk_fma_f32 v[20:21], v[20:21], v[172:173], v[24:25]
	v_pk_fma_f32 v[22:23], v[22:23], v[170:171], v[26:27]
	global_store_dwordx4 v[50:51], v[20:23], off offset:512
	s_waitcnt vmcnt(3)
	s_nop 0
	v_sub_f32_e32 v21, v45, v48
	v_sub_f32_e32 v20, v44, v48
	v_sub_f32_e32 v23, v47, v48
	v_sub_f32_e32 v22, v46, v48
	v_pk_mul_f32 v[22:23], v[52:53], v[22:23] op_sel_hi:[0,1]
	v_pk_mul_f32 v[20:21], v[52:53], v[20:21] op_sel_hi:[0,1]
	v_pk_fma_f32 v[20:21], v[64:65], v[20:21], v[168:169]
	v_pk_fma_f32 v[22:23], v[66:67], v[22:23], v[166:167]
	v_pk_fma_f32 v[16:17], v[16:17], v[164:165], v[20:21]
	v_pk_fma_f32 v[18:19], v[18:19], v[162:163], v[22:23]
	global_store_dwordx4 v[50:51], v[16:19], off offset:576
	s_and_b64 vcc, exec, s[6:7]
	s_cbranch_vccnz .Lmy_epi_w6
	s_sleep 50

.LBB0_1378:
	s_ashr_i32 s25, s76, 3
	s_mul_hi_i32 s35, s25, 0x9000
	s_mul_i32 s25, s25, 0x9000
	s_add_u32 s34, s12, s25
	s_addc_u32 s35, s13, s35
	s_lshl_b32 s25, s76, 8
	v_add_u32_e32 v194, s25, v151
	v_lshl_add_u64 v[128:129], s[20:21], 0, v[160:161]
	v_ashrrev_i32_e32 v195, 31, v194
	global_load_dwordx4 v[162:165], v[128:129], off
	v_lshl_add_u64 v[130:131], s[34:35], 0, v[160:161]
	global_load_dwordx4 v[170:173], v[128:129], off offset:64
	global_load_dwordx4 v[174:177], v[128:129], off offset:512
	global_load_dwordx4 v[178:181], v[130:131], off
	global_load_dwordx4 v[182:185], v[130:131], off offset:64
	global_load_dwordx4 v[232:235], v[128:129], off offset:576
	global_load_dwordx4 v[236:239], v[130:131], off offset:512
	global_load_dwordx4 v[240:243], v[130:131], off offset:576
	v_lshl_add_u64 v[128:129], v[194:195], 3, s[14:15]
	v_lshlrev_b64 v[166:167], 12, v[194:195]
	global_load_dwordx2 v[206:207], v[128:129], off
	v_lshl_add_u64 v[128:129], s[16:17], 0, v[166:167]
	v_lshl_add_u64 v[128:129], v[128:129], 0, v[160:161]
	global_load_dwordx4 v[244:247], v[128:129], off
	global_load_dwordx4 v[248:251], v[128:129], off offset:64
	global_load_dwordx4 v[216:219], v[128:129], off offset:512
	global_load_dwordx4 v[212:215], v[128:129], off offset:576
	v_lshl_add_u64 v[128:129], s[18:19], 0, v[160:161]
	global_load_dwordx4 v[140:143], v[128:129], off
	global_load_dwordx4 v[136:139], v[128:129], off offset:64
	global_load_dwordx4 v[132:135], v[128:129], off offset:512
	s_nop 0
	global_load_dwordx4 v[128:131], v[128:129], off offset:576
	v_lshl_add_u64 v[166:167], s[8:9], 0, v[166:167]
	v_lshl_add_u64 v[198:199], v[166:167], 0, v[160:161]
	s_waitcnt vmcnt(0)
	v_pk_mul_f32 v[168:169], v[172:173], s[58:59] op_sel_hi:[1,0]
	v_pk_mul_f32 v[188:189], v[170:171], s[58:59] op_sel_hi:[1,0]
	v_pk_mul_f32 v[170:171], v[176:177], s[58:59] op_sel_hi:[1,0]
	v_pk_fma_f32 v[176:177], v[178:179], 0.5, 0.5 op_sel_hi:[1,0,0]
	v_pk_mul_f32 v[172:173], v[234:235], s[58:59] op_sel_hi:[1,0]
	v_pk_mul_f32 v[192:193], v[232:233], s[58:59] op_sel_hi:[1,0]
	v_pk_fma_f32 v[178:179], v[184:185], 0.5, 0.5 op_sel_hi:[1,0,0]
	v_pk_fma_f32 v[184:185], v[236:237], 0.5, 0.5 op_sel_hi:[1,0,0]
	v_pk_mul_f32 v[166:167], v[164:165], s[58:59] op_sel_hi:[1,0]
	v_mul_f32_e32 v232, 0x3fb504f3, v207
	v_sub_f32_e32 v235, v245, v206
	v_sub_f32_e32 v234, v244, v206
	v_sub_f32_e32 v237, v247, v206
	v_sub_f32_e32 v236, v246, v206
	v_sub_f32_e32 v213, v213, v206
	v_sub_f32_e32 v212, v212, v206
	v_pk_mul_f32 v[186:187], v[162:163], s[58:59] op_sel_hi:[1,0]
	v_pk_mul_f32 v[190:191], v[174:175], s[58:59] op_sel_hi:[1,0]
	v_pk_fma_f32 v[174:175], v[180:181], 0.5, 0.5 op_sel_hi:[1,0,0]
	v_pk_fma_f32 v[180:181], v[182:183], 0.5, 0.5 op_sel_hi:[1,0,0]
	v_pk_fma_f32 v[182:183], v[238:239], 0.5, 0.5 op_sel_hi:[1,0,0]
	v_pk_fma_f32 v[164:165], v[240:241], 0.5, 0.5 op_sel_hi:[1,0,0]
	v_sub_f32_e32 v239, v249, v206
	v_sub_f32_e32 v238, v248, v206
	v_sub_f32_e32 v241, v251, v206
	v_sub_f32_e32 v240, v250, v206
	v_sub_f32_e32 v217, v217, v206
	v_sub_f32_e32 v216, v216, v206
	v_sub_f32_e32 v219, v219, v206
	v_sub_f32_e32 v218, v218, v206
	v_sub_f32_e32 v207, v215, v206
	v_sub_f32_e32 v206, v214, v206
	v_pk_mul_f32 v[214:215], v[236:237], v[232:233] op_sel_hi:[1,0]
	v_pk_mul_f32 v[234:235], v[234:235], v[232:233] op_sel_hi:[1,0]
	v_pk_mul_f32 v[212:213], v[232:233], v[212:213] op_sel_hi:[0,1]
	v_pk_mul_f32 v[236:237], v[240:241], v[232:233] op_sel_hi:[1,0]
	v_pk_mul_f32 v[238:239], v[238:239], v[232:233] op_sel_hi:[1,0]
	v_pk_mul_f32 v[218:219], v[232:233], v[218:219] op_sel_hi:[0,1]
	v_pk_mul_f32 v[216:217], v[232:233], v[216:217] op_sel_hi:[0,1]
	v_pk_mul_f32 v[206:207], v[232:233], v[206:207] op_sel_hi:[0,1]
	v_pk_fma_f32 v[232:233], v[140:141], v[234:235], v[186:187]
	v_pk_fma_f32 v[214:215], v[142:143], v[214:215], v[166:167]
	v_pk_fma_f32 v[212:213], v[128:129], v[212:213], v[192:193]
	v_pk_fma_f32 v[162:163], v[242:243], 0.5, 0.5 op_sel_hi:[1,0,0]
	v_pk_fma_f32 v[234:235], v[136:137], v[238:239], v[188:189]
	v_pk_fma_f32 v[236:237], v[138:139], v[236:237], v[168:169]
	v_pk_fma_f32 v[216:217], v[132:133], v[216:217], v[190:191]
	v_pk_fma_f32 v[218:219], v[134:135], v[218:219], v[170:171]
	v_pk_fma_f32 v[206:207], v[130:131], v[206:207], v[172:173]
	v_pk_fma_f32 v[126:127], v[126:127], v[174:175], v[214:215]
	v_pk_fma_f32 v[124:125], v[124:125], v[176:177], v[232:233]
	v_pk_fma_f32 v[112:113], v[112:113], v[164:165], v[212:213]
	v_pk_fma_f32 v[122:123], v[122:123], v[178:179], v[236:237]
	v_pk_fma_f32 v[120:121], v[120:121], v[180:181], v[234:235]
	v_pk_fma_f32 v[118:119], v[118:119], v[182:183], v[218:219]
	v_pk_fma_f32 v[116:117], v[116:117], v[184:185], v[216:217]
	v_pk_fma_f32 v[114:115], v[114:115], v[162:163], v[206:207]
	global_store_dwordx4 v[198:199], v[124:127], off
	global_store_dwordx4 v[198:199], v[120:123], off offset:64
	global_store_dwordx4 v[198:199], v[116:119], off offset:512
	global_store_dwordx4 v[198:199], v[112:115], off offset:576
	s_and_b64 vcc, exec, s[6:7]
	s_cbranch_vccnz .Lmy_epi_f0
	s_sleep 50
.Lmy_epi_f0:
	v_add_u32_e32 v212, s25, v227
	v_ashrrev_i32_e32 v213, 31, v212
	v_add_u32_e32 v112, s25, v226
	v_ashrrev_i32_e32 v113, 31, v112
	v_lshlrev_b64 v[206:207], 12, v[112:113]
	v_lshl_add_u64 v[114:115], v[112:113], 3, s[14:15]
	v_lshl_add_u64 v[112:113], s[16:17], 0, v[206:207]
	global_load_dwordx2 v[198:199], v[114:115], off
	v_lshl_add_u64 v[124:125], v[112:113], 0, v[160:161]
	global_load_dwordx4 v[112:115], v[124:125], off
	global_load_dwordx4 v[116:119], v[124:125], off offset:64
	global_load_dwordx4 v[120:123], v[124:125], off offset:512
	s_nop 0
	global_load_dwordx4 v[124:127], v[124:125], off offset:576
	v_lshl_add_u64 v[206:207], s[8:9], 0, v[206:207]
	v_lshl_add_u64 v[206:207], v[206:207], 0, v[160:161]
	v_lshl_add_u64 v[214:215], v[212:213], 3, s[14:15]
	v_lshlrev_b64 v[212:213], 12, v[212:213]
	v_lshl_add_u64 v[216:217], s[16:17], 0, v[212:213]
	v_lshl_add_u64 v[216:217], v[216:217], 0, v[160:161]
	s_waitcnt vmcnt(4)
	v_mul_f32_e32 v218, 0x3fb504f3, v199
	s_waitcnt vmcnt(3)
	v_sub_f32_e32 v113, v113, v198
	v_sub_f32_e32 v112, v112, v198
	v_sub_f32_e32 v115, v115, v198
	v_sub_f32_e32 v114, v114, v198
	s_waitcnt vmcnt(2)
	v_sub_f32_e32 v117, v117, v198
	v_sub_f32_e32 v116, v116, v198
	v_sub_f32_e32 v119, v119, v198
	v_sub_f32_e32 v118, v118, v198
	s_waitcnt vmcnt(1)
	v_sub_f32_e32 v121, v121, v198
	v_sub_f32_e32 v120, v120, v198
	v_sub_f32_e32 v123, v123, v198
	v_sub_f32_e32 v122, v122, v198
	s_waitcnt vmcnt(0)
	v_sub_f32_e32 v125, v125, v198
	v_sub_f32_e32 v124, v124, v198
	v_sub_f32_e32 v127, v127, v198
	v_sub_f32_e32 v126, v126, v198
	v_pk_mul_f32 v[114:115], v[114:115], v[218:219] op_sel_hi:[1,0]
	v_pk_mul_f32 v[112:113], v[112:113], v[218:219] op_sel_hi:[1,0]
	v_pk_mul_f32 v[118:119], v[118:119], v[218:219] op_sel_hi:[1,0]
	v_pk_mul_f32 v[116:117], v[116:117], v[218:219] op_sel_hi:[1,0]
	v_pk_mul_f32 v[122:123], v[218:219], v[122:123] op_sel_hi:[0,1]
	v_pk_mul_f32 v[120:121], v[218:219], v[120:121] op_sel_hi:[0,1]
	v_pk_mul_f32 v[126:127], v[218:219], v[126:127] op_sel_hi:[0,1]
	v_pk_mul_f32 v[124:125], v[218:219], v[124:125] op_sel_hi:[0,1]
	v_pk_fma_f32 v[112:113], v[140:141], v[112:113], v[186:187]
	v_pk_fma_f32 v[114:115], v[142:143], v[114:115], v[166:167]
	v_pk_fma_f32 v[116:117], v[136:137], v[116:117], v[188:189]
	v_pk_fma_f32 v[118:119], v[138:139], v[118:119], v[168:169]
	v_pk_fma_f32 v[120:121], v[132:133], v[120:121], v[190:191]
	v_pk_fma_f32 v[122:123], v[134:135], v[122:123], v[170:171]
	v_pk_fma_f32 v[124:125], v[128:129], v[124:125], v[192:193]
	v_pk_fma_f32 v[126:127], v[130:131], v[126:127], v[172:173]
	v_pk_fma_f32 v[110:111], v[110:111], v[174:175], v[114:115]
	v_pk_fma_f32 v[108:109], v[108:109], v[176:177], v[112:113]
	v_pk_fma_f32 v[106:107], v[106:107], v[178:179], v[118:119]
	v_pk_fma_f32 v[104:105], v[104:105], v[180:181], v[116:117]
	v_pk_fma_f32 v[102:103], v[102:103], v[182:183], v[122:123]
	v_pk_fma_f32 v[100:101], v[100:101], v[184:185], v[120:121]
	v_pk_fma_f32 v[98:99], v[98:99], v[162:163], v[126:127]
	v_pk_fma_f32 v[96:97], v[96:97], v[164:165], v[124:125]
	global_store_dwordx4 v[206:207], v[108:111], off
	global_store_dwordx4 v[206:207], v[104:107], off offset:64
	global_store_dwordx4 v[206:207], v[100:103], off offset:512
	global_store_dwordx4 v[206:207], v[96:99], off offset:576
	s_and_b64 vcc, exec, s[6:7]
	s_cbranch_vccnz .Lmy_epi_f1
	s_sleep 50
.Lmy_epi_f1:
	global_load_dwordx2 v[112:113], v[214:215], off
	global_load_dwordx4 v[96:99], v[216:217], off
	global_load_dwordx4 v[100:103], v[216:217], off offset:64
	global_load_dwordx4 v[104:107], v[216:217], off offset:512
	global_load_dwordx4 v[108:111], v[216:217], off offset:576
	v_add_u32_e32 v114, s25, v228
	v_lshl_add_u64 v[118:119], s[8:9], 0, v[212:213]
	v_ashrrev_i32_e32 v115, 31, v114
	v_lshl_add_u64 v[118:119], v[118:119], 0, v[160:161]
	v_lshl_add_u64 v[116:117], v[114:115], 3, s[14:15]
	v_lshlrev_b64 v[114:115], 12, v[114:115]
	v_lshl_add_u64 v[120:121], s[16:17], 0, v[114:115]
	v_lshl_add_u64 v[120:121], v[120:121], 0, v[160:161]
	s_waitcnt vmcnt(4)
	v_mul_f32_e32 v122, 0x3fb504f3, v113
	s_waitcnt vmcnt(3)
	v_sub_f32_e32 v97, v97, v112
	v_sub_f32_e32 v96, v96, v112
	v_sub_f32_e32 v99, v99, v112
	v_sub_f32_e32 v98, v98, v112
	s_waitcnt vmcnt(2)
	v_sub_f32_e32 v101, v101, v112
	v_sub_f32_e32 v100, v100, v112
	v_sub_f32_e32 v103, v103, v112
	v_sub_f32_e32 v102, v102, v112
	s_waitcnt vmcnt(1)
	v_sub_f32_e32 v105, v105, v112
	v_sub_f32_e32 v104, v104, v112
	v_sub_f32_e32 v107, v107, v112
	v_sub_f32_e32 v106, v106, v112
	s_waitcnt vmcnt(0)
	v_sub_f32_e32 v109, v109, v112
	v_sub_f32_e32 v108, v108, v112
	v_sub_f32_e32 v111, v111, v112
	v_sub_f32_e32 v110, v110, v112
	v_pk_mul_f32 v[98:99], v[98:99], v[122:123] op_sel_hi:[1,0]
	v_pk_mul_f32 v[96:97], v[96:97], v[122:123] op_sel_hi:[1,0]
	v_pk_mul_f32 v[102:103], v[102:103], v[122:123] op_sel_hi:[1,0]
	v_pk_mul_f32 v[100:101], v[100:101], v[122:123] op_sel_hi:[1,0]
	v_pk_mul_f32 v[106:107], v[122:123], v[106:107] op_sel_hi:[0,1]
	v_pk_mul_f32 v[104:105], v[122:123], v[104:105] op_sel_hi:[0,1]
	v_pk_mul_f32 v[110:111], v[122:123], v[110:111] op_sel_hi:[0,1]
	v_pk_mul_f32 v[108:109], v[122:123], v[108:109] op_sel_hi:[0,1]
	v_pk_fma_f32 v[96:97], v[140:141], v[96:97], v[186:187]
	v_pk_fma_f32 v[98:99], v[142:143], v[98:99], v[166:167]
	v_pk_fma_f32 v[100:101], v[136:137], v[100:101], v[188:189]
	v_pk_fma_f32 v[102:103], v[138:139], v[102:103], v[168:169]
	v_pk_fma_f32 v[104:105], v[132:133], v[104:105], v[190:191]
	v_pk_fma_f32 v[106:107], v[134:135], v[106:107], v[170:171]
	v_pk_fma_f32 v[108:109], v[128:129], v[108:109], v[192:193]
	v_pk_fma_f32 v[110:111], v[130:131], v[110:111], v[172:173]
	v_pk_fma_f32 v[94:95], v[94:95], v[174:175], v[98:99]
	v_pk_fma_f32 v[92:93], v[92:93], v[176:177], v[96:97]
	v_pk_fma_f32 v[90:91], v[90:91], v[178:179], v[102:103]
	v_pk_fma_f32 v[88:89], v[88:89], v[180:181], v[100:101]
	v_pk_fma_f32 v[86:87], v[86:87], v[182:183], v[106:107]
	v_pk_fma_f32 v[84:85], v[84:85], v[184:185], v[104:105]
	v_pk_fma_f32 v[82:83], v[82:83], v[162:163], v[110:111]
	v_pk_fma_f32 v[80:81], v[80:81], v[164:165], v[108:109]
	global_store_dwordx4 v[118:119], v[92:95], off
	global_store_dwordx4 v[118:119], v[88:91], off offset:64
	global_store_dwordx4 v[118:119], v[84:87], off offset:512
	global_store_dwordx4 v[118:119], v[80:83], off offset:576
	s_and_b64 vcc, exec, s[6:7]
	s_cbranch_vccnz .Lmy_epi_f2
	s_sleep 50
.Lmy_epi_f2:
	global_load_dwordx2 v[96:97], v[116:117], off
	global_load_dwordx4 v[80:83], v[120:121], off
	global_load_dwordx4 v[84:87], v[120:121], off offset:64
	global_load_dwordx4 v[88:91], v[120:121], off offset:512
	global_load_dwordx4 v[92:95], v[120:121], off offset:576
	v_add_u32_e32 v98, 0x80, v194
	v_lshl_add_u64 v[100:101], s[8:9], 0, v[114:115]
	v_ashrrev_i32_e32 v99, 31, v98
	v_lshl_add_u64 v[100:101], v[100:101], 0, v[160:161]
	v_lshl_add_u64 v[102:103], v[98:99], 3, s[14:15]
	v_lshlrev_b64 v[98:99], 12, v[98:99]
	v_lshl_add_u64 v[104:105], s[16:17], 0, v[98:99]
	v_lshl_add_u64 v[104:105], v[104:105], 0, v[160:161]
	s_waitcnt vmcnt(4)
	v_mul_f32_e32 v106, 0x3fb504f3, v97
	s_waitcnt vmcnt(3)
	v_sub_f32_e32 v81, v81, v96
	v_sub_f32_e32 v80, v80, v96
	v_sub_f32_e32 v83, v83, v96
	v_sub_f32_e32 v82, v82, v96
	s_waitcnt vmcnt(2)
	v_sub_f32_e32 v85, v85, v96
	v_sub_f32_e32 v84, v84, v96
	v_sub_f32_e32 v87, v87, v96
	v_sub_f32_e32 v86, v86, v96
	s_waitcnt vmcnt(1)
	v_sub_f32_e32 v89, v89, v96
	v_sub_f32_e32 v88, v88, v96
	v_sub_f32_e32 v91, v91, v96
	v_sub_f32_e32 v90, v90, v96
	s_waitcnt vmcnt(0)
	v_sub_f32_e32 v93, v93, v96
	v_sub_f32_e32 v92, v92, v96
	v_sub_f32_e32 v95, v95, v96
	v_sub_f32_e32 v94, v94, v96
	v_pk_mul_f32 v[82:83], v[82:83], v[106:107] op_sel_hi:[1,0]
	v_pk_mul_f32 v[80:81], v[80:81], v[106:107] op_sel_hi:[1,0]
	v_pk_mul_f32 v[86:87], v[86:87], v[106:107] op_sel_hi:[1,0]
	v_pk_mul_f32 v[84:85], v[84:85], v[106:107] op_sel_hi:[1,0]
	v_pk_mul_f32 v[90:91], v[106:107], v[90:91] op_sel_hi:[0,1]
	v_pk_mul_f32 v[88:89], v[106:107], v[88:89] op_sel_hi:[0,1]
	v_pk_mul_f32 v[94:95], v[106:107], v[94:95] op_sel_hi:[0,1]
	v_pk_mul_f32 v[92:93], v[106:107], v[92:93] op_sel_hi:[0,1]
	v_pk_fma_f32 v[80:81], v[140:141], v[80:81], v[186:187]
	v_pk_fma_f32 v[82:83], v[142:143], v[82:83], v[166:167]
	v_pk_fma_f32 v[84:85], v[136:137], v[84:85], v[188:189]
	v_pk_fma_f32 v[86:87], v[138:139], v[86:87], v[168:169]
	v_pk_fma_f32 v[88:89], v[132:133], v[88:89], v[190:191]
	v_pk_fma_f32 v[90:91], v[134:135], v[90:91], v[170:171]
	v_pk_fma_f32 v[92:93], v[128:129], v[92:93], v[192:193]
	v_pk_fma_f32 v[94:95], v[130:131], v[94:95], v[172:173]
	v_pk_fma_f32 v[78:79], v[78:79], v[174:175], v[82:83]
	v_pk_fma_f32 v[76:77], v[76:77], v[176:177], v[80:81]
	v_pk_fma_f32 v[74:75], v[74:75], v[178:179], v[86:87]
	v_pk_fma_f32 v[72:73], v[72:73], v[180:181], v[84:85]
	v_pk_fma_f32 v[70:71], v[70:71], v[182:183], v[90:91]
	v_pk_fma_f32 v[68:69], v[68:69], v[184:185], v[88:89]
	v_pk_fma_f32 v[66:67], v[66:67], v[162:163], v[94:95]
	v_pk_fma_f32 v[64:65], v[64:65], v[164:165], v[92:93]
	global_store_dwordx4 v[100:101], v[76:79], off
	global_store_dwordx4 v[100:101], v[72:75], off offset:64
	global_store_dwordx4 v[100:101], v[68:71], off offset:512
	global_store_dwordx4 v[100:101], v[64:67], off offset:576
	s_and_b64 vcc, exec, s[6:7]
	s_cbranch_vccnz .Lmy_epi_f3
	s_sleep 50
.Lmy_epi_f3:
	global_load_dwordx2 v[80:81], v[102:103], off
	global_load_dwordx4 v[64:67], v[104:105], off
	global_load_dwordx4 v[68:71], v[104:105], off offset:64
	global_load_dwordx4 v[72:75], v[104:105], off offset:512
	global_load_dwordx4 v[76:79], v[104:105], off offset:576
	v_add_u32_e32 v82, 0x90, v194
	v_lshl_add_u64 v[86:87], s[8:9], 0, v[98:99]
	v_ashrrev_i32_e32 v83, 31, v82
	v_lshl_add_u64 v[86:87], v[86:87], 0, v[160:161]
	v_lshl_add_u64 v[84:85], v[82:83], 3, s[14:15]
	v_lshlrev_b64 v[82:83], 12, v[82:83]
	v_lshl_add_u64 v[88:89], s[16:17], 0, v[82:83]
	v_lshl_add_u64 v[88:89], v[88:89], 0, v[160:161]
	s_waitcnt vmcnt(4)
	v_mul_f32_e32 v90, 0x3fb504f3, v81
	s_waitcnt vmcnt(3)
	v_sub_f32_e32 v65, v65, v80
	v_sub_f32_e32 v64, v64, v80
	v_sub_f32_e32 v67, v67, v80
	v_sub_f32_e32 v66, v66, v80
	s_waitcnt vmcnt(2)
	v_sub_f32_e32 v69, v69, v80
	v_sub_f32_e32 v68, v68, v80
	v_sub_f32_e32 v71, v71, v80
	v_sub_f32_e32 v70, v70, v80
	s_waitcnt vmcnt(1)
	v_sub_f32_e32 v73, v73, v80
	v_sub_f32_e32 v72, v72, v80
	v_sub_f32_e32 v75, v75, v80
	v_sub_f32_e32 v74, v74, v80
	s_waitcnt vmcnt(0)
	v_sub_f32_e32 v77, v77, v80
	v_sub_f32_e32 v76, v76, v80
	v_sub_f32_e32 v79, v79, v80
	v_sub_f32_e32 v78, v78, v80
	v_pk_mul_f32 v[66:67], v[66:67], v[90:91] op_sel_hi:[1,0]
	v_pk_mul_f32 v[64:65], v[64:65], v[90:91] op_sel_hi:[1,0]
	v_pk_mul_f32 v[70:71], v[70:71], v[90:91] op_sel_hi:[1,0]
	v_pk_mul_f32 v[68:69], v[68:69], v[90:91] op_sel_hi:[1,0]
	v_pk_mul_f32 v[74:75], v[90:91], v[74:75] op_sel_hi:[0,1]
	v_pk_mul_f32 v[72:73], v[90:91], v[72:73] op_sel_hi:[0,1]
	v_pk_mul_f32 v[78:79], v[90:91], v[78:79] op_sel_hi:[0,1]
	v_pk_mul_f32 v[76:77], v[90:91], v[76:77] op_sel_hi:[0,1]
	v_pk_fma_f32 v[64:65], v[140:141], v[64:65], v[186:187]
	v_pk_fma_f32 v[66:67], v[142:143], v[66:67], v[166:167]
	v_pk_fma_f32 v[68:69], v[136:137], v[68:69], v[188:189]
	v_pk_fma_f32 v[70:71], v[138:139], v[70:71], v[168:169]
	v_pk_fma_f32 v[72:73], v[132:133], v[72:73], v[190:191]
	v_pk_fma_f32 v[74:75], v[134:135], v[74:75], v[170:171]
	v_pk_fma_f32 v[76:77], v[128:129], v[76:77], v[192:193]
	v_pk_fma_f32 v[78:79], v[130:131], v[78:79], v[172:173]
	v_pk_fma_f32 v[62:63], v[62:63], v[174:175], v[66:67]
	v_pk_fma_f32 v[60:61], v[60:61], v[176:177], v[64:65]
	v_pk_fma_f32 v[58:59], v[58:59], v[178:179], v[70:71]
	v_pk_fma_f32 v[56:57], v[56:57], v[180:181], v[68:69]
	v_pk_fma_f32 v[54:55], v[54:55], v[182:183], v[74:75]
	v_pk_fma_f32 v[52:53], v[52:53], v[184:185], v[72:73]
	v_pk_fma_f32 v[50:51], v[50:51], v[162:163], v[78:79]
	v_pk_fma_f32 v[48:49], v[48:49], v[164:165], v[76:77]
	global_store_dwordx4 v[86:87], v[60:63], off
	global_store_dwordx4 v[86:87], v[56:59], off offset:64
	global_store_dwordx4 v[86:87], v[52:55], off offset:512
	global_store_dwordx4 v[86:87], v[48:51], off offset:576
	s_and_b64 vcc, exec, s[6:7]
	s_cbranch_vccnz .Lmy_epi_f4
	s_sleep 50
.Lmy_epi_f4:
	global_load_dwordx2 v[64:65], v[84:85], off
	global_load_dwordx4 v[48:51], v[88:89], off
	global_load_dwordx4 v[52:55], v[88:89], off offset:64
	global_load_dwordx4 v[56:59], v[88:89], off offset:512
	global_load_dwordx4 v[60:63], v[88:89], off offset:576
	v_add_u32_e32 v66, 0xa0, v194
	v_lshl_add_u64 v[70:71], s[8:9], 0, v[82:83]
	v_ashrrev_i32_e32 v67, 31, v66
	v_lshl_add_u64 v[70:71], v[70:71], 0, v[160:161]
	v_lshl_add_u64 v[68:69], v[66:67], 3, s[14:15]
	v_lshlrev_b64 v[66:67], 12, v[66:67]
	v_lshl_add_u64 v[72:73], s[16:17], 0, v[66:67]
	v_lshl_add_u64 v[72:73], v[72:73], 0, v[160:161]
	s_waitcnt vmcnt(4)
	v_mul_f32_e32 v74, 0x3fb504f3, v65
	s_waitcnt vmcnt(3)
	v_sub_f32_e32 v49, v49, v64
	v_sub_f32_e32 v48, v48, v64
	v_sub_f32_e32 v51, v51, v64
	v_sub_f32_e32 v50, v50, v64
	s_waitcnt vmcnt(2)
	v_sub_f32_e32 v53, v53, v64
	v_sub_f32_e32 v52, v52, v64
	v_sub_f32_e32 v55, v55, v64
	v_sub_f32_e32 v54, v54, v64
	s_waitcnt vmcnt(1)
	v_sub_f32_e32 v57, v57, v64
	v_sub_f32_e32 v56, v56, v64
	v_sub_f32_e32 v59, v59, v64
	v_sub_f32_e32 v58, v58, v64
	s_waitcnt vmcnt(0)
	v_sub_f32_e32 v61, v61, v64
	v_sub_f32_e32 v60, v60, v64
	v_sub_f32_e32 v63, v63, v64
	v_sub_f32_e32 v62, v62, v64
	v_pk_mul_f32 v[50:51], v[50:51], v[74:75] op_sel_hi:[1,0]
	v_pk_mul_f32 v[48:49], v[48:49], v[74:75] op_sel_hi:[1,0]
	v_pk_mul_f32 v[54:55], v[54:55], v[74:75] op_sel_hi:[1,0]
	v_pk_mul_f32 v[52:53], v[52:53], v[74:75] op_sel_hi:[1,0]
	v_pk_mul_f32 v[58:59], v[74:75], v[58:59] op_sel_hi:[0,1]
	v_pk_mul_f32 v[56:57], v[74:75], v[56:57] op_sel_hi:[0,1]
	v_pk_mul_f32 v[62:63], v[74:75], v[62:63] op_sel_hi:[0,1]
	v_pk_mul_f32 v[60:61], v[74:75], v[60:61] op_sel_hi:[0,1]
	v_pk_fma_f32 v[48:49], v[140:141], v[48:49], v[186:187]
	v_pk_fma_f32 v[50:51], v[142:143], v[50:51], v[166:167]
	v_pk_fma_f32 v[52:53], v[136:137], v[52:53], v[188:189]
	v_pk_fma_f32 v[54:55], v[138:139], v[54:55], v[168:169]
	v_pk_fma_f32 v[56:57], v[132:133], v[56:57], v[190:191]
	v_pk_fma_f32 v[58:59], v[134:135], v[58:59], v[170:171]
	v_pk_fma_f32 v[60:61], v[128:129], v[60:61], v[192:193]
	v_pk_fma_f32 v[62:63], v[130:131], v[62:63], v[172:173]
	v_pk_fma_f32 v[46:47], v[46:47], v[174:175], v[50:51]
	v_pk_fma_f32 v[44:45], v[44:45], v[176:177], v[48:49]
	v_pk_fma_f32 v[42:43], v[42:43], v[178:179], v[54:55]
	v_pk_fma_f32 v[40:41], v[40:41], v[180:181], v[52:53]
	v_pk_fma_f32 v[38:39], v[38:39], v[182:183], v[58:59]
	v_pk_fma_f32 v[36:37], v[36:37], v[184:185], v[56:57]
	v_pk_fma_f32 v[34:35], v[34:35], v[162:163], v[62:63]
	v_pk_fma_f32 v[32:33], v[32:33], v[164:165], v[60:61]
	global_store_dwordx4 v[70:71], v[44:47], off
	global_store_dwordx4 v[70:71], v[40:43], off offset:64
	global_store_dwordx4 v[70:71], v[36:39], off offset:512
	global_store_dwordx4 v[70:71], v[32:35], off offset:576
	s_and_b64 vcc, exec, s[6:7]
	s_cbranch_vccnz .Lmy_epi_f5
	s_sleep 50
.Lmy_epi_f5:
	global_load_dwordx2 v[48:49], v[68:69], off
	global_load_dwordx4 v[32:35], v[72:73], off
	global_load_dwordx4 v[36:39], v[72:73], off offset:64
	global_load_dwordx4 v[40:43], v[72:73], off offset:512
	global_load_dwordx4 v[44:47], v[72:73], off offset:576
	v_add_u32_e32 v50, 0xb0, v194
	v_lshl_add_u64 v[54:55], s[8:9], 0, v[66:67]
	v_ashrrev_i32_e32 v51, 31, v50
	v_lshl_add_u64 v[54:55], v[54:55], 0, v[160:161]
	v_lshl_add_u64 v[52:53], v[50:51], 3, s[14:15]
	v_lshlrev_b64 v[50:51], 12, v[50:51]
	v_lshl_add_u64 v[56:57], s[16:17], 0, v[50:51]
	v_lshl_add_u64 v[56:57], v[56:57], 0, v[160:161]
	s_waitcnt vmcnt(4)
	v_mul_f32_e32 v58, 0x3fb504f3, v49
	s_waitcnt vmcnt(3)
	v_sub_f32_e32 v33, v33, v48
	v_sub_f32_e32 v32, v32, v48
	v_sub_f32_e32 v35, v35, v48
	v_sub_f32_e32 v34, v34, v48
	s_waitcnt vmcnt(2)
	v_sub_f32_e32 v37, v37, v48
	v_sub_f32_e32 v36, v36, v48
	v_sub_f32_e32 v39, v39, v48
	v_sub_f32_e32 v38, v38, v48
	s_waitcnt vmcnt(1)
	v_sub_f32_e32 v41, v41, v48
	v_sub_f32_e32 v40, v40, v48
	v_sub_f32_e32 v43, v43, v48
	v_sub_f32_e32 v42, v42, v48
	s_waitcnt vmcnt(0)
	v_sub_f32_e32 v45, v45, v48
	v_sub_f32_e32 v44, v44, v48
	v_sub_f32_e32 v47, v47, v48
	v_sub_f32_e32 v46, v46, v48
	v_pk_mul_f32 v[34:35], v[34:35], v[58:59] op_sel_hi:[1,0]
	v_pk_mul_f32 v[32:33], v[32:33], v[58:59] op_sel_hi:[1,0]
	v_pk_mul_f32 v[38:39], v[38:39], v[58:59] op_sel_hi:[1,0]
	v_pk_mul_f32 v[36:37], v[36:37], v[58:59] op_sel_hi:[1,0]
	v_pk_mul_f32 v[42:43], v[58:59], v[42:43] op_sel_hi:[0,1]
	v_pk_mul_f32 v[40:41], v[58:59], v[40:41] op_sel_hi:[0,1]
	v_pk_mul_f32 v[46:47], v[58:59], v[46:47] op_sel_hi:[0,1]
	v_pk_mul_f32 v[44:45], v[58:59], v[44:45] op_sel_hi:[0,1]
	v_pk_fma_f32 v[32:33], v[140:141], v[32:33], v[186:187]
	v_pk_fma_f32 v[34:35], v[142:143], v[34:35], v[166:167]
	v_pk_fma_f32 v[36:37], v[136:137], v[36:37], v[188:189]
	v_pk_fma_f32 v[38:39], v[138:139], v[38:39], v[168:169]
	v_pk_fma_f32 v[40:41], v[132:133], v[40:41], v[190:191]
	v_pk_fma_f32 v[42:43], v[134:135], v[42:43], v[170:171]
	v_pk_fma_f32 v[44:45], v[128:129], v[44:45], v[192:193]
	v_pk_fma_f32 v[46:47], v[130:131], v[46:47], v[172:173]
	v_pk_fma_f32 v[30:31], v[30:31], v[174:175], v[34:35]
	v_pk_fma_f32 v[28:29], v[28:29], v[176:177], v[32:33]
	v_pk_fma_f32 v[26:27], v[26:27], v[178:179], v[38:39]
	v_pk_fma_f32 v[24:25], v[24:25], v[180:181], v[36:37]
	v_pk_fma_f32 v[22:23], v[22:23], v[182:183], v[42:43]
	v_pk_fma_f32 v[20:21], v[20:21], v[184:185], v[40:41]
	v_pk_fma_f32 v[18:19], v[18:19], v[162:163], v[46:47]
	v_pk_fma_f32 v[16:17], v[16:17], v[164:165], v[44:45]
	global_store_dwordx4 v[54:55], v[28:31], off
	global_store_dwordx4 v[54:55], v[24:27], off offset:64
	global_store_dwordx4 v[54:55], v[20:23], off offset:512
	global_store_dwordx4 v[54:55], v[16:19], off offset:576
	s_and_b64 vcc, exec, s[6:7]
	s_cbranch_vccnz .Lmy_epi_f6
	s_sleep 50
